# nt on read-once f32 cache tile loads in k2/k9 sample units
# baseline (speedup 1.0000x reference)
.LBB2_58:
	s_cmp_lt_u32 s88, s84
	s_cselect_b64 s[82:83], -1, 0
	s_cmp_ge_u32 s88, s84
	s_cbranch_scc1 .LBB2_66
	s_add_i32 s0, s94, -2
	s_cmp_ge_u32 s0, s85
	s_cbranch_scc1 .LBB2_61
	v_lshl_add_u64 v[38:39], v[162:163], 0, v[142:143]
	v_lshl_add_u64 v[46:47], v[158:159], 0, v[142:143]
	v_lshl_add_u64 v[54:55], v[156:157], 0, v[142:143]
	v_lshl_add_u64 v[62:63], v[152:153], 0, v[142:143]
	global_load_dwordx4 v[34:37], v[38:39], off nt
	s_nop 0
	global_load_dwordx4 v[38:41], v[38:39], off offset:16 nt
	s_nop 0
	global_load_dwordx4 v[42:45], v[46:47], off offset:-16 nt
	s_nop 0
	global_load_dwordx4 v[46:49], v[46:47], off nt
	s_nop 0
	global_load_dwordx4 v[50:53], v[54:55], off nt
	s_nop 0
	global_load_dwordx4 v[54:57], v[54:55], off offset:16 nt
	s_nop 0
	global_load_dwordx4 v[58:61], v[62:63], off offset:-16 nt
	s_nop 0
	global_load_dwordx4 v[62:65], v[62:63], off nt
	s_waitcnt vmcnt(7)
	v_cvt_pk_bf16_f32 v82, v34, v35
	v_cvt_pk_bf16_f32 v83, v36, v37
	s_waitcnt vmcnt(6)
	v_cvt_pk_bf16_f32 v84, v38, v39
	v_cvt_pk_bf16_f32 v85, v40, v41
	s_waitcnt vmcnt(5)
	v_cvt_pk_bf16_f32 v86, v42, v43
	v_cvt_pk_bf16_f32 v87, v44, v45
	s_waitcnt vmcnt(4)
	v_cvt_pk_bf16_f32 v88, v46, v47
	v_cvt_pk_bf16_f32 v89, v48, v49
	s_waitcnt vmcnt(3)
	v_cvt_pk_bf16_f32 v90, v50, v51
	v_cvt_pk_bf16_f32 v91, v52, v53
	s_waitcnt vmcnt(2)
	v_cvt_pk_bf16_f32 v92, v54, v55
	v_cvt_pk_bf16_f32 v93, v56, v57
	s_waitcnt vmcnt(1)
	v_cvt_pk_bf16_f32 v94, v58, v59
	v_cvt_pk_bf16_f32 v95, v60, v61
	s_waitcnt vmcnt(0)
	v_cvt_pk_bf16_f32 v96, v62, v63
	v_cvt_pk_bf16_f32 v97, v64, v65

.LBB2_84:
	s_andn2_b64 vcc, exec, s[74:75]
	s_cbranch_vccnz .LBB2_92
	s_cmp_ge_u32 s92, s85
	s_cbranch_scc1 .LBB2_87
	v_lshl_add_u64 v[38:39], v[172:173], 0, v[142:143]
	v_lshl_add_u64 v[46:47], v[170:171], 0, v[142:143]
	v_lshl_add_u64 v[54:55], v[168:169], 0, v[142:143]
	v_lshl_add_u64 v[62:63], v[166:167], 0, v[142:143]
	global_load_dwordx4 v[34:37], v[38:39], off nt
	s_nop 0
	global_load_dwordx4 v[38:41], v[38:39], off offset:16 nt
	s_nop 0
	global_load_dwordx4 v[42:45], v[46:47], off offset:-16 nt
	s_nop 0
	global_load_dwordx4 v[46:49], v[46:47], off nt
	s_nop 0
	global_load_dwordx4 v[50:53], v[54:55], off nt
	s_nop 0
	global_load_dwordx4 v[54:57], v[54:55], off offset:16 nt
	s_nop 0
	global_load_dwordx4 v[58:61], v[62:63], off offset:-16 nt
	s_nop 0
	global_load_dwordx4 v[62:65], v[62:63], off nt
	s_waitcnt vmcnt(7)
	v_cvt_pk_bf16_f32 v102, v34, v35
	v_cvt_pk_bf16_f32 v103, v36, v37
	s_waitcnt vmcnt(6)
	v_cvt_pk_bf16_f32 v104, v38, v39
	v_cvt_pk_bf16_f32 v105, v40, v41
	s_waitcnt vmcnt(5)
	v_cvt_pk_bf16_f32 v106, v42, v43
	v_cvt_pk_bf16_f32 v107, v44, v45
	s_waitcnt vmcnt(4)
	v_cvt_pk_bf16_f32 v108, v46, v47
	v_cvt_pk_bf16_f32 v109, v48, v49
	s_waitcnt vmcnt(3)
	v_cvt_pk_bf16_f32 v110, v50, v51
	v_cvt_pk_bf16_f32 v111, v52, v53
	s_waitcnt vmcnt(2)
	v_cvt_pk_bf16_f32 v112, v54, v55
	v_cvt_pk_bf16_f32 v113, v56, v57
	s_waitcnt vmcnt(1)
	v_cvt_pk_bf16_f32 v114, v58, v59
	v_cvt_pk_bf16_f32 v115, v60, v61
	s_waitcnt vmcnt(0)
	v_cvt_pk_bf16_f32 v116, v62, v63
	v_cvt_pk_bf16_f32 v117, v64, v65

.LBB2_138:
	s_cmp_lt_u32 s20, s26
	s_cselect_b64 s[14:15], -1, 0
	s_add_i32 s21, s19, -2
	s_cmp_ge_u32 s20, s26
	s_cbranch_scc1 .LBB2_144
	s_cmp_ge_u32 s21, s27
	s_cbranch_scc1 .LBB2_141
	v_lshl_add_u64 v[70:71], v[218:219], 0, v[202:203]
	v_lshl_add_u64 v[78:79], v[214:215], 0, v[202:203]
	v_lshl_add_u64 v[86:87], v[212:213], 0, v[202:203]
	v_lshl_add_u64 v[94:95], v[208:209], 0, v[202:203]
	global_load_dwordx4 v[66:69], v[70:71], off nt
	s_nop 0
	global_load_dwordx4 v[70:73], v[70:71], off offset:16 nt
	s_nop 0
	global_load_dwordx4 v[74:77], v[78:79], off offset:-16 nt
	s_nop 0
	global_load_dwordx4 v[78:81], v[78:79], off nt
	s_nop 0
	global_load_dwordx4 v[82:85], v[86:87], off nt
	s_nop 0
	global_load_dwordx4 v[86:89], v[86:87], off offset:16 nt
	s_nop 0
	global_load_dwordx4 v[90:93], v[94:95], off offset:-16 nt
	s_nop 0
	global_load_dwordx4 v[94:97], v[94:95], off nt
	s_waitcnt vmcnt(7)
	v_cvt_pk_bf16_f32 v118, v66, v67
	v_cvt_pk_bf16_f32 v119, v68, v69
	s_waitcnt vmcnt(6)
	v_cvt_pk_bf16_f32 v120, v70, v71
	v_cvt_pk_bf16_f32 v121, v72, v73
	s_waitcnt vmcnt(5)
	v_cvt_pk_bf16_f32 v122, v74, v75
	v_cvt_pk_bf16_f32 v123, v76, v77
	s_waitcnt vmcnt(4)
	v_cvt_pk_bf16_f32 v124, v78, v79
	v_cvt_pk_bf16_f32 v125, v80, v81
	s_waitcnt vmcnt(3)
	v_cvt_pk_bf16_f32 v126, v82, v83
	v_cvt_pk_bf16_f32 v127, v84, v85
	s_waitcnt vmcnt(2)
	v_cvt_pk_bf16_f32 v128, v86, v87
	v_cvt_pk_bf16_f32 v129, v88, v89
	s_waitcnt vmcnt(1)
	v_cvt_pk_bf16_f32 v130, v90, v91
	v_cvt_pk_bf16_f32 v131, v92, v93
	s_waitcnt vmcnt(0)
	v_cvt_pk_bf16_f32 v132, v94, v95
	v_cvt_pk_bf16_f32 v133, v96, v97

.LBB2_160:
	s_andn2_b64 vcc, exec, s[10:11]
	s_cbranch_vccnz .LBB2_166
	s_andn2_b64 vcc, exec, s[8:9]
	s_cbranch_vccnz .LBB2_163
	v_lshl_add_u64 v[70:71], v[228:229], 0, v[202:203]
	v_lshl_add_u64 v[78:79], v[230:231], 0, v[202:203]
	v_lshl_add_u64 v[86:87], v[226:227], 0, v[202:203]
	v_lshl_add_u64 v[94:95], v[224:225], 0, v[202:203]
	global_load_dwordx4 v[66:69], v[70:71], off offset:-16 nt
	s_nop 0
	global_load_dwordx4 v[70:73], v[70:71], off nt
	s_nop 0
	global_load_dwordx4 v[74:77], v[78:79], off offset:-16 nt
	s_nop 0
	global_load_dwordx4 v[78:81], v[78:79], off nt
	s_nop 0
	global_load_dwordx4 v[82:85], v[86:87], off nt
	s_nop 0
	global_load_dwordx4 v[86:89], v[86:87], off offset:16 nt
	s_nop 0
	global_load_dwordx4 v[90:93], v[94:95], off offset:-16 nt
	s_nop 0
	global_load_dwordx4 v[94:97], v[94:95], off nt
	s_waitcnt vmcnt(7)
	v_cvt_pk_bf16_f32 v134, v66, v67
	v_cvt_pk_bf16_f32 v135, v68, v69
	s_waitcnt vmcnt(6)
	v_cvt_pk_bf16_f32 v136, v70, v71
	v_cvt_pk_bf16_f32 v137, v72, v73
	s_waitcnt vmcnt(5)
	v_cvt_pk_bf16_f32 v138, v74, v75
	v_cvt_pk_bf16_f32 v139, v76, v77
	s_waitcnt vmcnt(4)
	v_cvt_pk_bf16_f32 v140, v78, v79
	v_cvt_pk_bf16_f32 v141, v80, v81
	s_waitcnt vmcnt(3)
	v_cvt_pk_bf16_f32 v142, v82, v83
	v_cvt_pk_bf16_f32 v143, v84, v85
	s_waitcnt vmcnt(2)
	v_cvt_pk_bf16_f32 v144, v86, v87
	v_cvt_pk_bf16_f32 v145, v88, v89
	s_waitcnt vmcnt(1)
	v_cvt_pk_bf16_f32 v146, v90, v91
	v_cvt_pk_bf16_f32 v147, v92, v93
	s_waitcnt vmcnt(0)
	v_cvt_pk_bf16_f32 v148, v94, v95
	v_cvt_pk_bf16_f32 v149, v96, v97

.LBB9_49:
	s_cmp_lt_i32 s66, s43
	s_cselect_b64 s[40:41], -1, 0
	s_cmp_ge_i32 s66, s43
	s_cbranch_scc1 .LBB9_55
	s_add_i32 s14, s65, 1
	s_cmp_ge_i32 s14, s60
	s_cbranch_scc1 .LBB9_54
	v_subrev_u32_e32 v70, 64, v136
	v_mad_i64_i32 v[36:37], s[38:39], s30, v70, 0
	v_or_b32_e32 v36, v36, v134
	v_lshlrev_b64 v[48:49], 2, v[36:37]
	v_lshl_add_u64 v[44:45], s[26:27], 0, v[48:49]
	s_lshl_b32 s14, s48, 2
	v_lshl_add_u64 v[56:57], s[28:29], 0, v[48:49]
	v_lshl_add_u64 v[50:51], v[44:45], 0, s[14:15]
	v_lshl_add_u64 v[64:65], v[56:57], 0, s[14:15]
	global_load_dwordx4 v[36:39], v[44:45], off offset:16 nt
	global_load_dwordx4 v[40:43], v[44:45], off nt
	s_nop 0
	global_load_dwordx4 v[44:47], v[50:51], off offset:16 nt
	global_load_dwordx4 v[52:55], v[50:51], off nt
	s_nop 0
	global_load_dwordx4 v[48:51], v[56:57], off offset:16 nt
	global_load_dwordx4 v[60:63], v[56:57], off nt
	s_nop 0
	global_load_dwordx4 v[56:59], v[64:65], off offset:16 nt
	s_nop 0
	global_load_dwordx4 v[64:67], v[64:65], off nt
	s_cmp_lt_i32 s65, 0
	s_cselect_b64 s[38:39], -1, 0
	s_xor_b64 s[68:69], s[6:7], -1
	s_or_b64 s[38:39], s[68:69], s[38:39]
	s_and_b64 vcc, exec, s[38:39]
	s_cbranch_vccnz .LBB9_53
	v_ashrrev_i32_e32 v71, 31, v70
	v_lshlrev_b64 v[70:71], 12, v[70:71]
	v_lshl_or_b32 v70, v134, 2, v70
	s_waitcnt vmcnt(11)
	v_lshl_add_u64 v[88:89], s[34:35], 0, v[70:71]
	s_waitcnt vmcnt(6)
	global_store_dwordx4 v[88:89], v[40:43], off nt
	global_store_dwordx4 v[88:89], v[36:39], off offset:16 nt
	v_lshl_add_u64 v[90:91], v[88:89], 0, s[18:19]
	v_add_co_u32_e32 v88, vcc, 0x20000, v88
	v_lshl_add_u64 v[70:71], s[36:37], 0, v[70:71]
	s_nop 0
	v_addc_co_u32_e32 v89, vcc, 0, v89, vcc
	s_waitcnt vmcnt(6)
	global_store_dwordx4 v[88:89], v[52:55], off nt
	global_store_dwordx4 v[90:91], v[44:47], off offset:16 nt
	s_waitcnt vmcnt(6)
	global_store_dwordx4 v[70:71], v[60:63], off nt
	global_store_dwordx4 v[70:71], v[48:51], off offset:16 nt
	v_lshl_add_u64 v[88:89], v[70:71], 0, s[18:19]
	v_add_co_u32_e32 v70, vcc, 0x20000, v70
	s_nop 1
	v_addc_co_u32_e32 v71, vcc, 0, v71, vcc
	s_waitcnt vmcnt(6)
	global_store_dwordx4 v[70:71], v[64:67], off nt
	global_store_dwordx4 v[88:89], v[56:59], off offset:16 nt

.LBB9_68:
	s_andn2_b64 vcc, exec, s[10:11]
	s_cbranch_vccnz .LBB9_74
	s_add_i32 s10, s65, 2
	s_cmp_ge_i32 s10, s60
	s_cbranch_scc1 .LBB9_73
	v_mad_i64_i32 v[36:37], s[10:11], s30, v136, 0
	v_or_b32_e32 v36, v36, v134
	v_lshlrev_b64 v[48:49], 2, v[36:37]
	v_lshl_add_u64 v[44:45], s[26:27], 0, v[48:49]
	s_lshl_b32 s14, s48, 2
	v_lshl_add_u64 v[56:57], s[28:29], 0, v[48:49]
	v_lshl_add_u64 v[50:51], v[44:45], 0, s[14:15]
	v_lshl_add_u64 v[64:65], v[56:57], 0, s[14:15]
	global_load_dwordx4 v[36:39], v[44:45], off offset:16 nt
	global_load_dwordx4 v[40:43], v[44:45], off nt
	s_nop 0
	global_load_dwordx4 v[44:47], v[50:51], off offset:16 nt
	global_load_dwordx4 v[52:55], v[50:51], off nt
	s_nop 0
	global_load_dwordx4 v[48:51], v[56:57], off offset:16 nt
	global_load_dwordx4 v[60:63], v[56:57], off nt
	s_nop 0
	global_load_dwordx4 v[56:59], v[64:65], off offset:16 nt
	s_nop 0
	global_load_dwordx4 v[64:67], v[64:65], off nt
	s_cmp_lt_i32 s65, -1
	s_cselect_b64 s[10:11], -1, 0
	s_xor_b64 s[38:39], s[6:7], -1
	s_or_b64 s[10:11], s[38:39], s[10:11]
	s_and_b64 vcc, exec, s[10:11]
	s_cbranch_vccnz .LBB9_72
	v_ashrrev_i32_e32 v137, 31, v136
	v_lshlrev_b64 v[70:71], 12, v[136:137]
	v_lshl_or_b32 v70, v134, 2, v70
	s_waitcnt vmcnt(11)
	v_lshl_add_u64 v[104:105], s[34:35], 0, v[70:71]
	s_waitcnt vmcnt(6)
	global_store_dwordx4 v[104:105], v[40:43], off nt
	global_store_dwordx4 v[104:105], v[36:39], off offset:16 nt
	v_lshl_add_u64 v[106:107], v[104:105], 0, s[18:19]
	v_add_co_u32_e32 v104, vcc, 0x20000, v104
	v_lshl_add_u64 v[70:71], s[36:37], 0, v[70:71]
	s_nop 0
	v_addc_co_u32_e32 v105, vcc, 0, v105, vcc
	s_waitcnt vmcnt(6)
	global_store_dwordx4 v[104:105], v[52:55], off nt
	global_store_dwordx4 v[106:107], v[44:47], off offset:16 nt
	s_waitcnt vmcnt(6)
	global_store_dwordx4 v[70:71], v[60:63], off nt
	global_store_dwordx4 v[70:71], v[48:51], off offset:16 nt
	v_lshl_add_u64 v[104:105], v[70:71], 0, s[18:19]
	v_add_co_u32_e32 v70, vcc, 0x20000, v70
	s_nop 1
	v_addc_co_u32_e32 v71, vcc, 0, v71, vcc
	s_waitcnt vmcnt(6)
	global_store_dwordx4 v[70:71], v[64:67], off nt
	global_store_dwordx4 v[104:105], v[56:59], off offset:16 nt

.LBB9_138:
	s_cmp_lt_i32 s69, s41
	s_cselect_b64 s[38:39], -1, 0
	s_cmp_ge_i32 s69, s41
	s_cbranch_scc1 .LBB9_144
	s_add_i32 s12, s68, 1
	s_cmp_ge_i32 s12, s63
	s_cbranch_scc1 .LBB9_143
	v_subrev_u32_e32 v70, 64, v136
	v_mad_i64_i32 v[36:37], s[36:37], s28, v70, 0
	v_or_b32_e32 v36, v36, v130
	v_lshlrev_b64 v[48:49], 2, v[36:37]
	v_lshl_add_u64 v[44:45], s[24:25], 0, v[48:49]
	s_lshl_b32 s12, s46, 2
	v_lshl_add_u64 v[56:57], s[26:27], 0, v[48:49]
	v_lshl_add_u64 v[50:51], v[44:45], 0, s[12:13]
	v_lshl_add_u64 v[64:65], v[56:57], 0, s[12:13]
	global_load_dwordx4 v[36:39], v[44:45], off offset:16 nt
	global_load_dwordx4 v[40:43], v[44:45], off nt
	s_nop 0
	global_load_dwordx4 v[44:47], v[50:51], off offset:16 nt
	global_load_dwordx4 v[52:55], v[50:51], off nt
	s_nop 0
	global_load_dwordx4 v[48:51], v[56:57], off offset:16 nt
	global_load_dwordx4 v[60:63], v[56:57], off nt
	s_nop 0
	global_load_dwordx4 v[56:59], v[64:65], off offset:16 nt
	s_nop 0
	global_load_dwordx4 v[64:67], v[64:65], off nt
	s_cmp_lt_i32 s68, 0
	s_cselect_b64 s[36:37], -1, 0
	s_xor_b64 s[72:73], s[4:5], -1
	s_or_b64 s[36:37], s[72:73], s[36:37]
	s_and_b64 vcc, exec, s[36:37]
	s_cbranch_vccnz .LBB9_142
	v_ashrrev_i32_e32 v71, 31, v70
	v_lshlrev_b64 v[70:71], 12, v[70:71]
	v_lshl_or_b32 v70, v130, 2, v70
	s_waitcnt vmcnt(11)
	v_lshl_add_u64 v[88:89], s[30:31], 0, v[70:71]
	s_waitcnt vmcnt(6)
	global_store_dwordx4 v[88:89], v[40:43], off nt
	global_store_dwordx4 v[88:89], v[36:39], off offset:16 nt
	v_lshl_add_u64 v[90:91], v[88:89], 0, s[16:17]
	v_add_co_u32_e32 v88, vcc, 0x20000, v88
	v_lshl_add_u64 v[70:71], s[34:35], 0, v[70:71]
	s_nop 0
	v_addc_co_u32_e32 v89, vcc, 0, v89, vcc
	s_waitcnt vmcnt(6)
	global_store_dwordx4 v[88:89], v[52:55], off nt
	global_store_dwordx4 v[90:91], v[44:47], off offset:16 nt
	s_waitcnt vmcnt(6)
	global_store_dwordx4 v[70:71], v[60:63], off nt
	global_store_dwordx4 v[70:71], v[48:51], off offset:16 nt
	v_lshl_add_u64 v[88:89], v[70:71], 0, s[16:17]
	v_add_co_u32_e32 v70, vcc, 0x20000, v70
	s_nop 1
	v_addc_co_u32_e32 v71, vcc, 0, v71, vcc
	s_waitcnt vmcnt(6)
	global_store_dwordx4 v[70:71], v[64:67], off nt
	global_store_dwordx4 v[88:89], v[56:59], off offset:16 nt
	s_nop 1
	v_cvt_pk_bf16_f32 v88, v40, v41
	v_cvt_pk_bf16_f32 v89, v42, v43
	v_cvt_pk_bf16_f32 v90, v36, v37
	v_cvt_pk_bf16_f32 v91, v38, v39
	v_cvt_pk_bf16_f32 v92, v52, v53
	v_cvt_pk_bf16_f32 v93, v54, v55
	v_cvt_pk_bf16_f32 v94, v44, v45
	v_cvt_pk_bf16_f32 v95, v46, v47
	v_cvt_pk_bf16_f32 v96, v60, v61
	v_cvt_pk_bf16_f32 v97, v62, v63
	v_cvt_pk_bf16_f32 v98, v48, v49
	v_cvt_pk_bf16_f32 v99, v50, v51
	v_cvt_pk_bf16_f32 v100, v64, v65
	v_cvt_pk_bf16_f32 v101, v66, v67
	v_cvt_pk_bf16_f32 v102, v56, v57
	v_cvt_pk_bf16_f32 v103, v58, v59
	ds_write_b128 v132, v[88:91] offset:17408
	ds_write_b128 v132, v[92:95] offset:26112
	ds_write_b128 v135, v[96:99]
	ds_write_b128 v135, v[100:103] offset:10240
	s_branch .LBB9_144

.LBB9_157:
	s_andn2_b64 vcc, exec, s[8:9]
	s_cbranch_vccnz .LBB9_163
	s_add_i32 s8, s68, 2
	s_cmp_ge_i32 s8, s63
	s_cbranch_scc1 .LBB9_162
	v_mad_i64_i32 v[36:37], s[8:9], s28, v136, 0
	v_or_b32_e32 v36, v36, v130
	v_lshlrev_b64 v[48:49], 2, v[36:37]
	v_lshl_add_u64 v[44:45], s[24:25], 0, v[48:49]
	s_lshl_b32 s12, s46, 2
	v_lshl_add_u64 v[56:57], s[26:27], 0, v[48:49]
	v_lshl_add_u64 v[50:51], v[44:45], 0, s[12:13]
	v_lshl_add_u64 v[64:65], v[56:57], 0, s[12:13]
	global_load_dwordx4 v[36:39], v[44:45], off offset:16 nt
	global_load_dwordx4 v[40:43], v[44:45], off nt
	s_nop 0
	global_load_dwordx4 v[44:47], v[50:51], off offset:16 nt
	global_load_dwordx4 v[52:55], v[50:51], off nt
	s_nop 0
	global_load_dwordx4 v[48:51], v[56:57], off offset:16 nt
	global_load_dwordx4 v[60:63], v[56:57], off nt
	s_nop 0
	global_load_dwordx4 v[56:59], v[64:65], off offset:16 nt
	s_nop 0
	global_load_dwordx4 v[64:67], v[64:65], off nt
	s_cmp_lt_i32 s68, -1
	s_cselect_b64 s[8:9], -1, 0
	s_xor_b64 s[36:37], s[4:5], -1
	s_or_b64 s[8:9], s[36:37], s[8:9]
	s_and_b64 vcc, exec, s[8:9]
	s_cbranch_vccnz .LBB9_161
	v_ashrrev_i32_e32 v137, 31, v136
	v_lshlrev_b64 v[70:71], 12, v[136:137]
	v_lshl_or_b32 v70, v130, 2, v70
	s_waitcnt vmcnt(11)
	v_lshl_add_u64 v[104:105], s[30:31], 0, v[70:71]
	s_waitcnt vmcnt(6)
	global_store_dwordx4 v[104:105], v[40:43], off nt
	global_store_dwordx4 v[104:105], v[36:39], off offset:16 nt
	v_lshl_add_u64 v[106:107], v[104:105], 0, s[16:17]
	v_add_co_u32_e32 v104, vcc, 0x20000, v104
	v_lshl_add_u64 v[70:71], s[34:35], 0, v[70:71]
	s_nop 0
	v_addc_co_u32_e32 v105, vcc, 0, v105, vcc
	s_waitcnt vmcnt(6)
	global_store_dwordx4 v[104:105], v[52:55], off nt
	global_store_dwordx4 v[106:107], v[44:47], off offset:16 nt
	s_waitcnt vmcnt(6)
	global_store_dwordx4 v[70:71], v[60:63], off nt
	global_store_dwordx4 v[70:71], v[48:51], off offset:16 nt
	v_lshl_add_u64 v[104:105], v[70:71], 0, s[16:17]
	v_add_co_u32_e32 v70, vcc, 0x20000, v70
	s_nop 1
	v_addc_co_u32_e32 v71, vcc, 0, v71, vcc
	s_waitcnt vmcnt(6)
	global_store_dwordx4 v[70:71], v[64:67], off nt
	global_store_dwordx4 v[104:105], v[56:59], off offset:16 nt
	s_nop 1
	v_cvt_pk_bf16_f32 v104, v40, v41
	v_cvt_pk_bf16_f32 v105, v42, v43
	v_cvt_pk_bf16_f32 v106, v36, v37
	v_cvt_pk_bf16_f32 v107, v38, v39
	v_cvt_pk_bf16_f32 v108, v52, v53
	v_cvt_pk_bf16_f32 v109, v54, v55
	v_cvt_pk_bf16_f32 v110, v44, v45
	v_cvt_pk_bf16_f32 v111, v46, v47
	v_cvt_pk_bf16_f32 v112, v60, v61
	v_cvt_pk_bf16_f32 v113, v62, v63
	v_cvt_pk_bf16_f32 v114, v48, v49
	v_cvt_pk_bf16_f32 v115, v50, v51
	v_cvt_pk_bf16_f32 v116, v64, v65
	v_cvt_pk_bf16_f32 v117, v66, v67
	v_cvt_pk_bf16_f32 v118, v56, v57
	v_cvt_pk_bf16_f32 v119, v58, v59
	ds_write_b128 v132, v[104:107]
	ds_write_b128 v132, v[108:111] offset:8704
	ds_write_b128 v134, v[112:115] offset:34816
	ds_write_b128 v134, v[116:119] offset:45056
	s_branch .LBB9_163
